# scan recurrence: the 32 steps of a chunk written out straight-line (no per-8-step base updates / loop control) and y partials of two steps leave in one ds_write2st64_b32
# speedup vs baseline: 1.0273x; 1.0134x over previous
.LBB0_619:
	s_and_saveexec_b64 s[0:1], s[8:9]
	s_xor_b64 s[14:15], exec, s[0:1]
	s_cbranch_execz .LBB0_623
	v_and_b32_e32 v87, 1, v101
	v_mad_u32_u24 v0, v87, s75, 0
	v_lshl_add_u32 v84, v98, 2, v0
	v_lshl_add_u32 v85, v99, 2, v0
	v_lshl_add_u32 v86, v87, 14, v162
	ds_read_b128 v[2:5], v84 offset:0
	ds_read_b128 v[6:9], v84 offset:8192
	ds_read_b128 v[10:13], v84 offset:16384
	ds_read_b128 v[14:17], v84 offset:24576
	ds_read_b128 v[18:21], v84 offset:32768
	ds_read_b32 v22, v85 offset:40960
	ds_read_b128 v[24:27], v84 offset:256
	ds_read_b128 v[28:31], v84 offset:8448
	ds_read_b128 v[32:35], v84 offset:16640
	ds_read_b128 v[36:39], v84 offset:24832
	ds_read_b128 v[40:43], v84 offset:33024
	ds_read_b32 v44, v85 offset:41024
	v_add_u32_e32 v86, 0x15000, v86
	s_waitcnt lgkmcnt(6)
	v_pk_mul_f32 v[68:69], v[2:3], v[78:79]
	v_pk_mul_f32 v[70:71], v[22:23], v[14:15] op_sel_hi:[0,1]
	v_pk_mul_f32 v[72:73], v[22:23], v[16:17] op_sel_hi:[0,1]
	v_pk_fma_f32 v[68:69], v[4:5], v[80:81], v[68:69]
	v_pk_fma_f32 v[74:75], v[6:7], v[78:79], v[70:71]
	v_pk_fma_f32 v[76:77], v[8:9], v[80:81], v[72:73]
	v_add_f32_e32 v68, v68, v69
	ds_read_b128 v[46:49], v84 offset:512
	ds_read_b128 v[50:53], v84 offset:8704
	v_add_f32_dpp v68, v68, v68 quad_perm:[1,0,3,2] row_mask:0xf bank_mask:0xf bound_ctrl:1
	ds_read_b128 v[54:57], v84 offset:16896
	ds_read_b128 v[58:61], v84 offset:25088
	v_add_f32_dpp v68, v68, v68 quad_perm:[2,3,0,1] row_mask:0xf bank_mask:0xf bound_ctrl:1
	ds_read_b128 v[62:65], v84 offset:33280
	ds_read_b32 v66, v85 offset:41088
	v_add_f32_dpp v68, v68, v68 row_half_mirror row_mask:0xf bank_mask:0xf bound_ctrl:1
	s_nop 1
	v_add_f32_dpp v68, v68, v68 row_ror:8 row_mask:0xf bank_mask:0xf bound_ctrl:1
	v_pk_fma_f32 v[78:79], v[10:11], v[68:69], v[74:75] op_sel_hi:[1,0,1] neg_lo:[0,1,0] neg_hi:[0,1,0]
	v_pk_fma_f32 v[80:81], v[12:13], v[68:69], v[76:77] op_sel_hi:[1,0,1] neg_lo:[0,1,0] neg_hi:[0,1,0]
	s_waitcnt lgkmcnt(6)
	v_pk_mul_f32 v[68:69], v[24:25], v[78:79]
	v_pk_mul_f32 v[82:83], v[18:19], v[78:79]
	v_pk_mul_f32 v[70:71], v[44:45], v[36:37] op_sel_hi:[0,1]
	v_pk_fma_f32 v[68:69], v[26:27], v[80:81], v[68:69]
	v_pk_fma_f32 v[82:83], v[20:21], v[80:81], v[82:83]
	v_pk_mul_f32 v[72:73], v[44:45], v[38:39] op_sel_hi:[0,1]
	v_add_f32_e32 v68, v68, v69
	v_add_f32_e32 v82, v82, v83
	v_pk_fma_f32 v[74:75], v[28:29], v[78:79], v[70:71]
	v_add_f32_dpp v68, v68, v68 quad_perm:[1,0,3,2] row_mask:0xf bank_mask:0xf bound_ctrl:1
	v_add_f32_dpp v82, v82, v82 row_ror:8 row_mask:0xf bank_mask:0xf bound_ctrl:1
	v_pk_fma_f32 v[76:77], v[30:31], v[80:81], v[72:73]
	v_add_f32_dpp v68, v68, v68 quad_perm:[2,3,0,1] row_mask:0xf bank_mask:0xf bound_ctrl:1
	ds_read_b128 v[106:109], v84 offset:768
	v_add_f32_dpp v68, v68, v68 row_half_mirror row_mask:0xf bank_mask:0xf bound_ctrl:1
	ds_read_b128 v[110:113], v84 offset:8960
	ds_read_b128 v[114:117], v84 offset:17152
	v_add_f32_dpp v68, v68, v68 row_ror:8 row_mask:0xf bank_mask:0xf bound_ctrl:1
	ds_read_b128 v[118:121], v84 offset:25344
	ds_read_b128 v[122:125], v84 offset:33536
	ds_read_b32 v126, v85 offset:41152
	v_pk_fma_f32 v[78:79], v[32:33], v[68:69], v[74:75] op_sel_hi:[1,0,1] neg_lo:[0,1,0] neg_hi:[0,1,0]
	v_pk_fma_f32 v[80:81], v[34:35], v[68:69], v[76:77] op_sel_hi:[1,0,1] neg_lo:[0,1,0] neg_hi:[0,1,0]
	s_waitcnt lgkmcnt(6)
	v_pk_mul_f32 v[68:69], v[46:47], v[78:79]
	v_pk_mul_f32 v[88:89], v[40:41], v[78:79]
	v_pk_mul_f32 v[70:71], v[66:67], v[58:59] op_sel_hi:[0,1]
	v_pk_fma_f32 v[68:69], v[48:49], v[80:81], v[68:69]
	v_pk_fma_f32 v[88:89], v[42:43], v[80:81], v[88:89]
	v_pk_mul_f32 v[72:73], v[66:67], v[60:61] op_sel_hi:[0,1]
	v_add_f32_e32 v68, v68, v69
	v_add_f32_e32 v88, v88, v89
	v_pk_fma_f32 v[74:75], v[50:51], v[78:79], v[70:71]
	v_add_f32_dpp v68, v68, v68 quad_perm:[1,0,3,2] row_mask:0xf bank_mask:0xf bound_ctrl:1
	v_add_f32_dpp v88, v88, v88 row_ror:8 row_mask:0xf bank_mask:0xf bound_ctrl:1
	v_pk_fma_f32 v[76:77], v[52:53], v[80:81], v[72:73]
	v_add_f32_dpp v68, v68, v68 quad_perm:[2,3,0,1] row_mask:0xf bank_mask:0xf bound_ctrl:1
	ds_write2st64_b32 v86, v82, v88 offset0:0 offset1:2
	ds_read_b128 v[2:5], v84 offset:1024
	v_add_f32_dpp v68, v68, v68 row_half_mirror row_mask:0xf bank_mask:0xf bound_ctrl:1
	ds_read_b128 v[6:9], v84 offset:9216
	ds_read_b128 v[10:13], v84 offset:17408
	v_add_f32_dpp v68, v68, v68 row_ror:8 row_mask:0xf bank_mask:0xf bound_ctrl:1
	ds_read_b128 v[14:17], v84 offset:25600
	ds_read_b128 v[18:21], v84 offset:33792
	ds_read_b32 v22, v85 offset:41216
	v_pk_fma_f32 v[78:79], v[54:55], v[68:69], v[74:75] op_sel_hi:[1,0,1] neg_lo:[0,1,0] neg_hi:[0,1,0]
	v_pk_fma_f32 v[80:81], v[56:57], v[68:69], v[76:77] op_sel_hi:[1,0,1] neg_lo:[0,1,0] neg_hi:[0,1,0]
	s_waitcnt lgkmcnt(6)
	v_pk_mul_f32 v[68:69], v[106:107], v[78:79]
	v_pk_mul_f32 v[82:83], v[62:63], v[78:79]
	v_pk_mul_f32 v[70:71], v[126:127], v[118:119] op_sel_hi:[0,1]
	v_pk_fma_f32 v[68:69], v[108:109], v[80:81], v[68:69]
	v_pk_fma_f32 v[82:83], v[64:65], v[80:81], v[82:83]
	v_pk_mul_f32 v[72:73], v[126:127], v[120:121] op_sel_hi:[0,1]
	v_add_f32_e32 v68, v68, v69
	v_add_f32_e32 v82, v82, v83
	v_pk_fma_f32 v[74:75], v[110:111], v[78:79], v[70:71]
	v_add_f32_dpp v68, v68, v68 quad_perm:[1,0,3,2] row_mask:0xf bank_mask:0xf bound_ctrl:1
	v_add_f32_dpp v82, v82, v82 row_ror:8 row_mask:0xf bank_mask:0xf bound_ctrl:1
	v_pk_fma_f32 v[76:77], v[112:113], v[80:81], v[72:73]
	v_add_f32_dpp v68, v68, v68 quad_perm:[2,3,0,1] row_mask:0xf bank_mask:0xf bound_ctrl:1
	ds_read_b128 v[24:27], v84 offset:1280
	v_add_f32_dpp v68, v68, v68 row_half_mirror row_mask:0xf bank_mask:0xf bound_ctrl:1
	ds_read_b128 v[28:31], v84 offset:9472
	ds_read_b128 v[32:35], v84 offset:17664
	v_add_f32_dpp v68, v68, v68 row_ror:8 row_mask:0xf bank_mask:0xf bound_ctrl:1
	ds_read_b128 v[36:39], v84 offset:25856
	ds_read_b128 v[40:43], v84 offset:34048
	ds_read_b32 v44, v85 offset:41280
	v_pk_fma_f32 v[78:79], v[114:115], v[68:69], v[74:75] op_sel_hi:[1,0,1] neg_lo:[0,1,0] neg_hi:[0,1,0]
	v_pk_fma_f32 v[80:81], v[116:117], v[68:69], v[76:77] op_sel_hi:[1,0,1] neg_lo:[0,1,0] neg_hi:[0,1,0]
	s_waitcnt lgkmcnt(6)
	v_pk_mul_f32 v[68:69], v[2:3], v[78:79]
	v_pk_mul_f32 v[88:89], v[122:123], v[78:79]
	v_pk_mul_f32 v[70:71], v[22:23], v[14:15] op_sel_hi:[0,1]
	v_pk_fma_f32 v[68:69], v[4:5], v[80:81], v[68:69]
	v_pk_fma_f32 v[88:89], v[124:125], v[80:81], v[88:89]
	v_pk_mul_f32 v[72:73], v[22:23], v[16:17] op_sel_hi:[0,1]
	v_add_f32_e32 v68, v68, v69
	v_add_f32_e32 v88, v88, v89
	v_pk_fma_f32 v[74:75], v[6:7], v[78:79], v[70:71]
	v_add_f32_dpp v68, v68, v68 quad_perm:[1,0,3,2] row_mask:0xf bank_mask:0xf bound_ctrl:1
	v_add_f32_dpp v88, v88, v88 row_ror:8 row_mask:0xf bank_mask:0xf bound_ctrl:1
	v_pk_fma_f32 v[76:77], v[8:9], v[80:81], v[72:73]
	v_add_f32_dpp v68, v68, v68 quad_perm:[2,3,0,1] row_mask:0xf bank_mask:0xf bound_ctrl:1
	ds_write2st64_b32 v86, v82, v88 offset0:4 offset1:6
	ds_read_b128 v[46:49], v84 offset:1536
	v_add_f32_dpp v68, v68, v68 row_half_mirror row_mask:0xf bank_mask:0xf bound_ctrl:1
	ds_read_b128 v[50:53], v84 offset:9728
	ds_read_b128 v[54:57], v84 offset:17920
	v_add_f32_dpp v68, v68, v68 row_ror:8 row_mask:0xf bank_mask:0xf bound_ctrl:1
	ds_read_b128 v[58:61], v84 offset:26112
	ds_read_b128 v[62:65], v84 offset:34304
	ds_read_b32 v66, v85 offset:41344
	v_pk_fma_f32 v[78:79], v[10:11], v[68:69], v[74:75] op_sel_hi:[1,0,1] neg_lo:[0,1,0] neg_hi:[0,1,0]
	v_pk_fma_f32 v[80:81], v[12:13], v[68:69], v[76:77] op_sel_hi:[1,0,1] neg_lo:[0,1,0] neg_hi:[0,1,0]
	s_waitcnt lgkmcnt(6)
	v_pk_mul_f32 v[68:69], v[24:25], v[78:79]
	v_pk_mul_f32 v[82:83], v[18:19], v[78:79]
	v_pk_mul_f32 v[70:71], v[44:45], v[36:37] op_sel_hi:[0,1]
	v_pk_fma_f32 v[68:69], v[26:27], v[80:81], v[68:69]
	v_pk_fma_f32 v[82:83], v[20:21], v[80:81], v[82:83]
	v_pk_mul_f32 v[72:73], v[44:45], v[38:39] op_sel_hi:[0,1]
	v_add_f32_e32 v68, v68, v69
	v_add_f32_e32 v82, v82, v83
	v_pk_fma_f32 v[74:75], v[28:29], v[78:79], v[70:71]
	v_add_f32_dpp v68, v68, v68 quad_perm:[1,0,3,2] row_mask:0xf bank_mask:0xf bound_ctrl:1
	v_add_f32_dpp v82, v82, v82 row_ror:8 row_mask:0xf bank_mask:0xf bound_ctrl:1
	v_pk_fma_f32 v[76:77], v[30:31], v[80:81], v[72:73]
	v_add_f32_dpp v68, v68, v68 quad_perm:[2,3,0,1] row_mask:0xf bank_mask:0xf bound_ctrl:1
	ds_read_b128 v[106:109], v84 offset:1792
	v_add_f32_dpp v68, v68, v68 row_half_mirror row_mask:0xf bank_mask:0xf bound_ctrl:1
	ds_read_b128 v[110:113], v84 offset:9984
	ds_read_b128 v[114:117], v84 offset:18176
	v_add_f32_dpp v68, v68, v68 row_ror:8 row_mask:0xf bank_mask:0xf bound_ctrl:1
	ds_read_b128 v[118:121], v84 offset:26368
	ds_read_b128 v[122:125], v84 offset:34560
	ds_read_b32 v126, v85 offset:41408
	v_pk_fma_f32 v[78:79], v[32:33], v[68:69], v[74:75] op_sel_hi:[1,0,1] neg_lo:[0,1,0] neg_hi:[0,1,0]
	v_pk_fma_f32 v[80:81], v[34:35], v[68:69], v[76:77] op_sel_hi:[1,0,1] neg_lo:[0,1,0] neg_hi:[0,1,0]
	s_waitcnt lgkmcnt(6)
	v_pk_mul_f32 v[68:69], v[46:47], v[78:79]
	v_pk_mul_f32 v[88:89], v[40:41], v[78:79]
	v_pk_mul_f32 v[70:71], v[66:67], v[58:59] op_sel_hi:[0,1]
	v_pk_fma_f32 v[68:69], v[48:49], v[80:81], v[68:69]
	v_pk_fma_f32 v[88:89], v[42:43], v[80:81], v[88:89]
	v_pk_mul_f32 v[72:73], v[66:67], v[60:61] op_sel_hi:[0,1]
	v_add_f32_e32 v68, v68, v69
	v_add_f32_e32 v88, v88, v89
	v_pk_fma_f32 v[74:75], v[50:51], v[78:79], v[70:71]
	v_add_f32_dpp v68, v68, v68 quad_perm:[1,0,3,2] row_mask:0xf bank_mask:0xf bound_ctrl:1
	v_add_f32_dpp v88, v88, v88 row_ror:8 row_mask:0xf bank_mask:0xf bound_ctrl:1
	v_pk_fma_f32 v[76:77], v[52:53], v[80:81], v[72:73]
	v_add_f32_dpp v68, v68, v68 quad_perm:[2,3,0,1] row_mask:0xf bank_mask:0xf bound_ctrl:1
	ds_write2st64_b32 v86, v82, v88 offset0:8 offset1:10
	ds_read_b128 v[2:5], v84 offset:2048
	v_add_f32_dpp v68, v68, v68 row_half_mirror row_mask:0xf bank_mask:0xf bound_ctrl:1
	ds_read_b128 v[6:9], v84 offset:10240
	ds_read_b128 v[10:13], v84 offset:18432
	v_add_f32_dpp v68, v68, v68 row_ror:8 row_mask:0xf bank_mask:0xf bound_ctrl:1
	ds_read_b128 v[14:17], v84 offset:26624
	ds_read_b128 v[18:21], v84 offset:34816
	ds_read_b32 v22, v85 offset:41472
	v_pk_fma_f32 v[78:79], v[54:55], v[68:69], v[74:75] op_sel_hi:[1,0,1] neg_lo:[0,1,0] neg_hi:[0,1,0]
	v_pk_fma_f32 v[80:81], v[56:57], v[68:69], v[76:77] op_sel_hi:[1,0,1] neg_lo:[0,1,0] neg_hi:[0,1,0]
	s_waitcnt lgkmcnt(6)
	v_pk_mul_f32 v[68:69], v[106:107], v[78:79]
	v_pk_mul_f32 v[82:83], v[62:63], v[78:79]
	v_pk_mul_f32 v[70:71], v[126:127], v[118:119] op_sel_hi:[0,1]
	v_pk_fma_f32 v[68:69], v[108:109], v[80:81], v[68:69]
	v_pk_fma_f32 v[82:83], v[64:65], v[80:81], v[82:83]
	v_pk_mul_f32 v[72:73], v[126:127], v[120:121] op_sel_hi:[0,1]
	v_add_f32_e32 v68, v68, v69
	v_add_f32_e32 v82, v82, v83
	v_pk_fma_f32 v[74:75], v[110:111], v[78:79], v[70:71]
	v_add_f32_dpp v68, v68, v68 quad_perm:[1,0,3,2] row_mask:0xf bank_mask:0xf bound_ctrl:1
	v_add_f32_dpp v82, v82, v82 row_ror:8 row_mask:0xf bank_mask:0xf bound_ctrl:1
	v_pk_fma_f32 v[76:77], v[112:113], v[80:81], v[72:73]
	v_add_f32_dpp v68, v68, v68 quad_perm:[2,3,0,1] row_mask:0xf bank_mask:0xf bound_ctrl:1
	ds_read_b128 v[24:27], v84 offset:2304
	v_add_f32_dpp v68, v68, v68 row_half_mirror row_mask:0xf bank_mask:0xf bound_ctrl:1
	ds_read_b128 v[28:31], v84 offset:10496
	ds_read_b128 v[32:35], v84 offset:18688
	v_add_f32_dpp v68, v68, v68 row_ror:8 row_mask:0xf bank_mask:0xf bound_ctrl:1
	ds_read_b128 v[36:39], v84 offset:26880
	ds_read_b128 v[40:43], v84 offset:35072
	ds_read_b32 v44, v85 offset:41536
	v_pk_fma_f32 v[78:79], v[114:115], v[68:69], v[74:75] op_sel_hi:[1,0,1] neg_lo:[0,1,0] neg_hi:[0,1,0]
	v_pk_fma_f32 v[80:81], v[116:117], v[68:69], v[76:77] op_sel_hi:[1,0,1] neg_lo:[0,1,0] neg_hi:[0,1,0]
	s_waitcnt lgkmcnt(6)
	v_pk_mul_f32 v[68:69], v[2:3], v[78:79]
	v_pk_mul_f32 v[88:89], v[122:123], v[78:79]
	v_pk_mul_f32 v[70:71], v[22:23], v[14:15] op_sel_hi:[0,1]
	v_pk_fma_f32 v[68:69], v[4:5], v[80:81], v[68:69]
	v_pk_fma_f32 v[88:89], v[124:125], v[80:81], v[88:89]
	v_pk_mul_f32 v[72:73], v[22:23], v[16:17] op_sel_hi:[0,1]
	v_add_f32_e32 v68, v68, v69
	v_add_f32_e32 v88, v88, v89
	v_pk_fma_f32 v[74:75], v[6:7], v[78:79], v[70:71]
	v_add_f32_dpp v68, v68, v68 quad_perm:[1,0,3,2] row_mask:0xf bank_mask:0xf bound_ctrl:1
	v_add_f32_dpp v88, v88, v88 row_ror:8 row_mask:0xf bank_mask:0xf bound_ctrl:1
	v_pk_fma_f32 v[76:77], v[8:9], v[80:81], v[72:73]
	v_add_f32_dpp v68, v68, v68 quad_perm:[2,3,0,1] row_mask:0xf bank_mask:0xf bound_ctrl:1
	ds_write2st64_b32 v86, v82, v88 offset0:12 offset1:14
	ds_read_b128 v[46:49], v84 offset:2560
	v_add_f32_dpp v68, v68, v68 row_half_mirror row_mask:0xf bank_mask:0xf bound_ctrl:1
	ds_read_b128 v[50:53], v84 offset:10752
	ds_read_b128 v[54:57], v84 offset:18944
	v_add_f32_dpp v68, v68, v68 row_ror:8 row_mask:0xf bank_mask:0xf bound_ctrl:1
	ds_read_b128 v[58:61], v84 offset:27136
	ds_read_b128 v[62:65], v84 offset:35328
	ds_read_b32 v66, v85 offset:41600
	v_pk_fma_f32 v[78:79], v[10:11], v[68:69], v[74:75] op_sel_hi:[1,0,1] neg_lo:[0,1,0] neg_hi:[0,1,0]
	v_pk_fma_f32 v[80:81], v[12:13], v[68:69], v[76:77] op_sel_hi:[1,0,1] neg_lo:[0,1,0] neg_hi:[0,1,0]
	s_waitcnt lgkmcnt(6)
	v_pk_mul_f32 v[68:69], v[24:25], v[78:79]
	v_pk_mul_f32 v[82:83], v[18:19], v[78:79]
	v_pk_mul_f32 v[70:71], v[44:45], v[36:37] op_sel_hi:[0,1]
	v_pk_fma_f32 v[68:69], v[26:27], v[80:81], v[68:69]
	v_pk_fma_f32 v[82:83], v[20:21], v[80:81], v[82:83]
	v_pk_mul_f32 v[72:73], v[44:45], v[38:39] op_sel_hi:[0,1]
	v_add_f32_e32 v68, v68, v69
	v_add_f32_e32 v82, v82, v83
	v_pk_fma_f32 v[74:75], v[28:29], v[78:79], v[70:71]
	v_add_f32_dpp v68, v68, v68 quad_perm:[1,0,3,2] row_mask:0xf bank_mask:0xf bound_ctrl:1
	v_add_f32_dpp v82, v82, v82 row_ror:8 row_mask:0xf bank_mask:0xf bound_ctrl:1
	v_pk_fma_f32 v[76:77], v[30:31], v[80:81], v[72:73]
	v_add_f32_dpp v68, v68, v68 quad_perm:[2,3,0,1] row_mask:0xf bank_mask:0xf bound_ctrl:1
	ds_read_b128 v[106:109], v84 offset:2816
	v_add_f32_dpp v68, v68, v68 row_half_mirror row_mask:0xf bank_mask:0xf bound_ctrl:1
	ds_read_b128 v[110:113], v84 offset:11008
	ds_read_b128 v[114:117], v84 offset:19200
	v_add_f32_dpp v68, v68, v68 row_ror:8 row_mask:0xf bank_mask:0xf bound_ctrl:1
	ds_read_b128 v[118:121], v84 offset:27392
	ds_read_b128 v[122:125], v84 offset:35584
	ds_read_b32 v126, v85 offset:41664
	v_pk_fma_f32 v[78:79], v[32:33], v[68:69], v[74:75] op_sel_hi:[1,0,1] neg_lo:[0,1,0] neg_hi:[0,1,0]
	v_pk_fma_f32 v[80:81], v[34:35], v[68:69], v[76:77] op_sel_hi:[1,0,1] neg_lo:[0,1,0] neg_hi:[0,1,0]
	s_waitcnt lgkmcnt(6)
	v_pk_mul_f32 v[68:69], v[46:47], v[78:79]
	v_pk_mul_f32 v[88:89], v[40:41], v[78:79]
	v_pk_mul_f32 v[70:71], v[66:67], v[58:59] op_sel_hi:[0,1]
	v_pk_fma_f32 v[68:69], v[48:49], v[80:81], v[68:69]
	v_pk_fma_f32 v[88:89], v[42:43], v[80:81], v[88:89]
	v_pk_mul_f32 v[72:73], v[66:67], v[60:61] op_sel_hi:[0,1]
	v_add_f32_e32 v68, v68, v69
	v_add_f32_e32 v88, v88, v89
	v_pk_fma_f32 v[74:75], v[50:51], v[78:79], v[70:71]
	v_add_f32_dpp v68, v68, v68 quad_perm:[1,0,3,2] row_mask:0xf bank_mask:0xf bound_ctrl:1
	v_add_f32_dpp v88, v88, v88 row_ror:8 row_mask:0xf bank_mask:0xf bound_ctrl:1
	v_pk_fma_f32 v[76:77], v[52:53], v[80:81], v[72:73]
	v_add_f32_dpp v68, v68, v68 quad_perm:[2,3,0,1] row_mask:0xf bank_mask:0xf bound_ctrl:1
	ds_write2st64_b32 v86, v82, v88 offset0:16 offset1:18
	ds_read_b128 v[2:5], v84 offset:3072
	v_add_f32_dpp v68, v68, v68 row_half_mirror row_mask:0xf bank_mask:0xf bound_ctrl:1
	ds_read_b128 v[6:9], v84 offset:11264
	ds_read_b128 v[10:13], v84 offset:19456
	v_add_f32_dpp v68, v68, v68 row_ror:8 row_mask:0xf bank_mask:0xf bound_ctrl:1
	ds_read_b128 v[14:17], v84 offset:27648
	ds_read_b128 v[18:21], v84 offset:35840
	ds_read_b32 v22, v85 offset:41728
	v_pk_fma_f32 v[78:79], v[54:55], v[68:69], v[74:75] op_sel_hi:[1,0,1] neg_lo:[0,1,0] neg_hi:[0,1,0]
	v_pk_fma_f32 v[80:81], v[56:57], v[68:69], v[76:77] op_sel_hi:[1,0,1] neg_lo:[0,1,0] neg_hi:[0,1,0]
	s_waitcnt lgkmcnt(6)
	v_pk_mul_f32 v[68:69], v[106:107], v[78:79]
	v_pk_mul_f32 v[82:83], v[62:63], v[78:79]
	v_pk_mul_f32 v[70:71], v[126:127], v[118:119] op_sel_hi:[0,1]
	v_pk_fma_f32 v[68:69], v[108:109], v[80:81], v[68:69]
	v_pk_fma_f32 v[82:83], v[64:65], v[80:81], v[82:83]
	v_pk_mul_f32 v[72:73], v[126:127], v[120:121] op_sel_hi:[0,1]
	v_add_f32_e32 v68, v68, v69
	v_add_f32_e32 v82, v82, v83
	v_pk_fma_f32 v[74:75], v[110:111], v[78:79], v[70:71]
	v_add_f32_dpp v68, v68, v68 quad_perm:[1,0,3,2] row_mask:0xf bank_mask:0xf bound_ctrl:1
	v_add_f32_dpp v82, v82, v82 row_ror:8 row_mask:0xf bank_mask:0xf bound_ctrl:1
	v_pk_fma_f32 v[76:77], v[112:113], v[80:81], v[72:73]
	v_add_f32_dpp v68, v68, v68 quad_perm:[2,3,0,1] row_mask:0xf bank_mask:0xf bound_ctrl:1
	ds_read_b128 v[24:27], v84 offset:3328
	v_add_f32_dpp v68, v68, v68 row_half_mirror row_mask:0xf bank_mask:0xf bound_ctrl:1
	ds_read_b128 v[28:31], v84 offset:11520
	ds_read_b128 v[32:35], v84 offset:19712
	v_add_f32_dpp v68, v68, v68 row_ror:8 row_mask:0xf bank_mask:0xf bound_ctrl:1
	ds_read_b128 v[36:39], v84 offset:27904
	ds_read_b128 v[40:43], v84 offset:36096
	ds_read_b32 v44, v85 offset:41792
	v_pk_fma_f32 v[78:79], v[114:115], v[68:69], v[74:75] op_sel_hi:[1,0,1] neg_lo:[0,1,0] neg_hi:[0,1,0]
	v_pk_fma_f32 v[80:81], v[116:117], v[68:69], v[76:77] op_sel_hi:[1,0,1] neg_lo:[0,1,0] neg_hi:[0,1,0]
	s_waitcnt lgkmcnt(6)
	v_pk_mul_f32 v[68:69], v[2:3], v[78:79]
	v_pk_mul_f32 v[88:89], v[122:123], v[78:79]
	v_pk_mul_f32 v[70:71], v[22:23], v[14:15] op_sel_hi:[0,1]
	v_pk_fma_f32 v[68:69], v[4:5], v[80:81], v[68:69]
	v_pk_fma_f32 v[88:89], v[124:125], v[80:81], v[88:89]
	v_pk_mul_f32 v[72:73], v[22:23], v[16:17] op_sel_hi:[0,1]
	v_add_f32_e32 v68, v68, v69
	v_add_f32_e32 v88, v88, v89
	v_pk_fma_f32 v[74:75], v[6:7], v[78:79], v[70:71]
	v_add_f32_dpp v68, v68, v68 quad_perm:[1,0,3,2] row_mask:0xf bank_mask:0xf bound_ctrl:1
	v_add_f32_dpp v88, v88, v88 row_ror:8 row_mask:0xf bank_mask:0xf bound_ctrl:1
	v_pk_fma_f32 v[76:77], v[8:9], v[80:81], v[72:73]
	v_add_f32_dpp v68, v68, v68 quad_perm:[2,3,0,1] row_mask:0xf bank_mask:0xf bound_ctrl:1
	ds_write2st64_b32 v86, v82, v88 offset0:20 offset1:22
	ds_read_b128 v[46:49], v84 offset:3584
	v_add_f32_dpp v68, v68, v68 row_half_mirror row_mask:0xf bank_mask:0xf bound_ctrl:1
	ds_read_b128 v[50:53], v84 offset:11776
	ds_read_b128 v[54:57], v84 offset:19968
	v_add_f32_dpp v68, v68, v68 row_ror:8 row_mask:0xf bank_mask:0xf bound_ctrl:1
	ds_read_b128 v[58:61], v84 offset:28160
	ds_read_b128 v[62:65], v84 offset:36352
	ds_read_b32 v66, v85 offset:41856
	v_pk_fma_f32 v[78:79], v[10:11], v[68:69], v[74:75] op_sel_hi:[1,0,1] neg_lo:[0,1,0] neg_hi:[0,1,0]
	v_pk_fma_f32 v[80:81], v[12:13], v[68:69], v[76:77] op_sel_hi:[1,0,1] neg_lo:[0,1,0] neg_hi:[0,1,0]
	s_waitcnt lgkmcnt(6)
	v_pk_mul_f32 v[68:69], v[24:25], v[78:79]
	v_pk_mul_f32 v[82:83], v[18:19], v[78:79]
	v_pk_mul_f32 v[70:71], v[44:45], v[36:37] op_sel_hi:[0,1]
	v_pk_fma_f32 v[68:69], v[26:27], v[80:81], v[68:69]
	v_pk_fma_f32 v[82:83], v[20:21], v[80:81], v[82:83]
	v_pk_mul_f32 v[72:73], v[44:45], v[38:39] op_sel_hi:[0,1]
	v_add_f32_e32 v68, v68, v69
	v_add_f32_e32 v82, v82, v83
	v_pk_fma_f32 v[74:75], v[28:29], v[78:79], v[70:71]
	v_add_f32_dpp v68, v68, v68 quad_perm:[1,0,3,2] row_mask:0xf bank_mask:0xf bound_ctrl:1
	v_add_f32_dpp v82, v82, v82 row_ror:8 row_mask:0xf bank_mask:0xf bound_ctrl:1
	v_pk_fma_f32 v[76:77], v[30:31], v[80:81], v[72:73]
	v_add_f32_dpp v68, v68, v68 quad_perm:[2,3,0,1] row_mask:0xf bank_mask:0xf bound_ctrl:1
	ds_read_b128 v[106:109], v84 offset:3840
	v_add_f32_dpp v68, v68, v68 row_half_mirror row_mask:0xf bank_mask:0xf bound_ctrl:1
	ds_read_b128 v[110:113], v84 offset:12032
	ds_read_b128 v[114:117], v84 offset:20224
	v_add_f32_dpp v68, v68, v68 row_ror:8 row_mask:0xf bank_mask:0xf bound_ctrl:1
	ds_read_b128 v[118:121], v84 offset:28416
	ds_read_b128 v[122:125], v84 offset:36608
	ds_read_b32 v126, v85 offset:41920
	v_pk_fma_f32 v[78:79], v[32:33], v[68:69], v[74:75] op_sel_hi:[1,0,1] neg_lo:[0,1,0] neg_hi:[0,1,0]
	v_pk_fma_f32 v[80:81], v[34:35], v[68:69], v[76:77] op_sel_hi:[1,0,1] neg_lo:[0,1,0] neg_hi:[0,1,0]
	s_waitcnt lgkmcnt(6)
	v_pk_mul_f32 v[68:69], v[46:47], v[78:79]
	v_pk_mul_f32 v[88:89], v[40:41], v[78:79]
	v_pk_mul_f32 v[70:71], v[66:67], v[58:59] op_sel_hi:[0,1]
	v_pk_fma_f32 v[68:69], v[48:49], v[80:81], v[68:69]
	v_pk_fma_f32 v[88:89], v[42:43], v[80:81], v[88:89]
	v_pk_mul_f32 v[72:73], v[66:67], v[60:61] op_sel_hi:[0,1]
	v_add_f32_e32 v68, v68, v69
	v_add_f32_e32 v88, v88, v89
	v_pk_fma_f32 v[74:75], v[50:51], v[78:79], v[70:71]
	v_add_f32_dpp v68, v68, v68 quad_perm:[1,0,3,2] row_mask:0xf bank_mask:0xf bound_ctrl:1
	v_add_f32_dpp v88, v88, v88 row_ror:8 row_mask:0xf bank_mask:0xf bound_ctrl:1
	v_pk_fma_f32 v[76:77], v[52:53], v[80:81], v[72:73]
	v_add_f32_dpp v68, v68, v68 quad_perm:[2,3,0,1] row_mask:0xf bank_mask:0xf bound_ctrl:1
	ds_write2st64_b32 v86, v82, v88 offset0:24 offset1:26
	ds_read_b128 v[2:5], v84 offset:4096
	v_add_f32_dpp v68, v68, v68 row_half_mirror row_mask:0xf bank_mask:0xf bound_ctrl:1
	ds_read_b128 v[6:9], v84 offset:12288
	ds_read_b128 v[10:13], v84 offset:20480
	v_add_f32_dpp v68, v68, v68 row_ror:8 row_mask:0xf bank_mask:0xf bound_ctrl:1
	ds_read_b128 v[14:17], v84 offset:28672
	ds_read_b128 v[18:21], v84 offset:36864
	ds_read_b32 v22, v85 offset:41984
	v_pk_fma_f32 v[78:79], v[54:55], v[68:69], v[74:75] op_sel_hi:[1,0,1] neg_lo:[0,1,0] neg_hi:[0,1,0]
	v_pk_fma_f32 v[80:81], v[56:57], v[68:69], v[76:77] op_sel_hi:[1,0,1] neg_lo:[0,1,0] neg_hi:[0,1,0]
	s_waitcnt lgkmcnt(6)
	v_pk_mul_f32 v[68:69], v[106:107], v[78:79]
	v_pk_mul_f32 v[82:83], v[62:63], v[78:79]
	v_pk_mul_f32 v[70:71], v[126:127], v[118:119] op_sel_hi:[0,1]
	v_pk_fma_f32 v[68:69], v[108:109], v[80:81], v[68:69]
	v_pk_fma_f32 v[82:83], v[64:65], v[80:81], v[82:83]
	v_pk_mul_f32 v[72:73], v[126:127], v[120:121] op_sel_hi:[0,1]
	v_add_f32_e32 v68, v68, v69
	v_add_f32_e32 v82, v82, v83
	v_pk_fma_f32 v[74:75], v[110:111], v[78:79], v[70:71]
	v_add_f32_dpp v68, v68, v68 quad_perm:[1,0,3,2] row_mask:0xf bank_mask:0xf bound_ctrl:1
	v_add_f32_dpp v82, v82, v82 row_ror:8 row_mask:0xf bank_mask:0xf bound_ctrl:1
	v_pk_fma_f32 v[76:77], v[112:113], v[80:81], v[72:73]
	v_add_f32_dpp v68, v68, v68 quad_perm:[2,3,0,1] row_mask:0xf bank_mask:0xf bound_ctrl:1
	ds_read_b128 v[24:27], v84 offset:4352
	v_add_f32_dpp v68, v68, v68 row_half_mirror row_mask:0xf bank_mask:0xf bound_ctrl:1
	ds_read_b128 v[28:31], v84 offset:12544
	ds_read_b128 v[32:35], v84 offset:20736
	v_add_f32_dpp v68, v68, v68 row_ror:8 row_mask:0xf bank_mask:0xf bound_ctrl:1
	ds_read_b128 v[36:39], v84 offset:28928
	ds_read_b128 v[40:43], v84 offset:37120
	ds_read_b32 v44, v85 offset:42048
	v_pk_fma_f32 v[78:79], v[114:115], v[68:69], v[74:75] op_sel_hi:[1,0,1] neg_lo:[0,1,0] neg_hi:[0,1,0]
	v_pk_fma_f32 v[80:81], v[116:117], v[68:69], v[76:77] op_sel_hi:[1,0,1] neg_lo:[0,1,0] neg_hi:[0,1,0]
	s_waitcnt lgkmcnt(6)
	v_pk_mul_f32 v[68:69], v[2:3], v[78:79]
	v_pk_mul_f32 v[88:89], v[122:123], v[78:79]
	v_pk_mul_f32 v[70:71], v[22:23], v[14:15] op_sel_hi:[0,1]
	v_pk_fma_f32 v[68:69], v[4:5], v[80:81], v[68:69]
	v_pk_fma_f32 v[88:89], v[124:125], v[80:81], v[88:89]
	v_pk_mul_f32 v[72:73], v[22:23], v[16:17] op_sel_hi:[0,1]
	v_add_f32_e32 v68, v68, v69
	v_add_f32_e32 v88, v88, v89
	v_pk_fma_f32 v[74:75], v[6:7], v[78:79], v[70:71]
	v_add_f32_dpp v68, v68, v68 quad_perm:[1,0,3,2] row_mask:0xf bank_mask:0xf bound_ctrl:1
	v_add_f32_dpp v88, v88, v88 row_ror:8 row_mask:0xf bank_mask:0xf bound_ctrl:1
	v_pk_fma_f32 v[76:77], v[8:9], v[80:81], v[72:73]
	v_add_f32_dpp v68, v68, v68 quad_perm:[2,3,0,1] row_mask:0xf bank_mask:0xf bound_ctrl:1
	ds_write2st64_b32 v86, v82, v88 offset0:28 offset1:30
	ds_read_b128 v[46:49], v84 offset:4608
	v_add_f32_dpp v68, v68, v68 row_half_mirror row_mask:0xf bank_mask:0xf bound_ctrl:1
	ds_read_b128 v[50:53], v84 offset:12800
	ds_read_b128 v[54:57], v84 offset:20992
	v_add_f32_dpp v68, v68, v68 row_ror:8 row_mask:0xf bank_mask:0xf bound_ctrl:1
	ds_read_b128 v[58:61], v84 offset:29184
	ds_read_b128 v[62:65], v84 offset:37376
	ds_read_b32 v66, v85 offset:42112
	v_pk_fma_f32 v[78:79], v[10:11], v[68:69], v[74:75] op_sel_hi:[1,0,1] neg_lo:[0,1,0] neg_hi:[0,1,0]
	v_pk_fma_f32 v[80:81], v[12:13], v[68:69], v[76:77] op_sel_hi:[1,0,1] neg_lo:[0,1,0] neg_hi:[0,1,0]
	s_waitcnt lgkmcnt(6)
	v_pk_mul_f32 v[68:69], v[24:25], v[78:79]
	v_pk_mul_f32 v[82:83], v[18:19], v[78:79]
	v_pk_mul_f32 v[70:71], v[44:45], v[36:37] op_sel_hi:[0,1]
	v_pk_fma_f32 v[68:69], v[26:27], v[80:81], v[68:69]
	v_pk_fma_f32 v[82:83], v[20:21], v[80:81], v[82:83]
	v_pk_mul_f32 v[72:73], v[44:45], v[38:39] op_sel_hi:[0,1]
	v_add_f32_e32 v68, v68, v69
	v_add_f32_e32 v82, v82, v83
	v_pk_fma_f32 v[74:75], v[28:29], v[78:79], v[70:71]
	v_add_f32_dpp v68, v68, v68 quad_perm:[1,0,3,2] row_mask:0xf bank_mask:0xf bound_ctrl:1
	v_add_f32_dpp v82, v82, v82 row_ror:8 row_mask:0xf bank_mask:0xf bound_ctrl:1
	v_pk_fma_f32 v[76:77], v[30:31], v[80:81], v[72:73]
	v_add_f32_dpp v68, v68, v68 quad_perm:[2,3,0,1] row_mask:0xf bank_mask:0xf bound_ctrl:1
	ds_read_b128 v[106:109], v84 offset:4864
	v_add_f32_dpp v68, v68, v68 row_half_mirror row_mask:0xf bank_mask:0xf bound_ctrl:1
	ds_read_b128 v[110:113], v84 offset:13056
	ds_read_b128 v[114:117], v84 offset:21248
	v_add_f32_dpp v68, v68, v68 row_ror:8 row_mask:0xf bank_mask:0xf bound_ctrl:1
	ds_read_b128 v[118:121], v84 offset:29440
	ds_read_b128 v[122:125], v84 offset:37632
	ds_read_b32 v126, v85 offset:42176
	v_pk_fma_f32 v[78:79], v[32:33], v[68:69], v[74:75] op_sel_hi:[1,0,1] neg_lo:[0,1,0] neg_hi:[0,1,0]
	v_pk_fma_f32 v[80:81], v[34:35], v[68:69], v[76:77] op_sel_hi:[1,0,1] neg_lo:[0,1,0] neg_hi:[0,1,0]
	s_waitcnt lgkmcnt(6)
	v_pk_mul_f32 v[68:69], v[46:47], v[78:79]
	v_pk_mul_f32 v[88:89], v[40:41], v[78:79]
	v_pk_mul_f32 v[70:71], v[66:67], v[58:59] op_sel_hi:[0,1]
	v_pk_fma_f32 v[68:69], v[48:49], v[80:81], v[68:69]
	v_pk_fma_f32 v[88:89], v[42:43], v[80:81], v[88:89]
	v_pk_mul_f32 v[72:73], v[66:67], v[60:61] op_sel_hi:[0,1]
	v_add_f32_e32 v68, v68, v69
	v_add_f32_e32 v88, v88, v89
	v_pk_fma_f32 v[74:75], v[50:51], v[78:79], v[70:71]
	v_add_f32_dpp v68, v68, v68 quad_perm:[1,0,3,2] row_mask:0xf bank_mask:0xf bound_ctrl:1
	v_add_f32_dpp v88, v88, v88 row_ror:8 row_mask:0xf bank_mask:0xf bound_ctrl:1
	v_pk_fma_f32 v[76:77], v[52:53], v[80:81], v[72:73]
	v_add_f32_dpp v68, v68, v68 quad_perm:[2,3,0,1] row_mask:0xf bank_mask:0xf bound_ctrl:1
	ds_write2st64_b32 v86, v82, v88 offset0:32 offset1:34
	ds_read_b128 v[2:5], v84 offset:5120
	v_add_f32_dpp v68, v68, v68 row_half_mirror row_mask:0xf bank_mask:0xf bound_ctrl:1
	ds_read_b128 v[6:9], v84 offset:13312
	ds_read_b128 v[10:13], v84 offset:21504
	v_add_f32_dpp v68, v68, v68 row_ror:8 row_mask:0xf bank_mask:0xf bound_ctrl:1
	ds_read_b128 v[14:17], v84 offset:29696
	ds_read_b128 v[18:21], v84 offset:37888
	ds_read_b32 v22, v85 offset:42240
	v_pk_fma_f32 v[78:79], v[54:55], v[68:69], v[74:75] op_sel_hi:[1,0,1] neg_lo:[0,1,0] neg_hi:[0,1,0]
	v_pk_fma_f32 v[80:81], v[56:57], v[68:69], v[76:77] op_sel_hi:[1,0,1] neg_lo:[0,1,0] neg_hi:[0,1,0]
	s_waitcnt lgkmcnt(6)
	v_pk_mul_f32 v[68:69], v[106:107], v[78:79]
	v_pk_mul_f32 v[82:83], v[62:63], v[78:79]
	v_pk_mul_f32 v[70:71], v[126:127], v[118:119] op_sel_hi:[0,1]
	v_pk_fma_f32 v[68:69], v[108:109], v[80:81], v[68:69]
	v_pk_fma_f32 v[82:83], v[64:65], v[80:81], v[82:83]
	v_pk_mul_f32 v[72:73], v[126:127], v[120:121] op_sel_hi:[0,1]
	v_add_f32_e32 v68, v68, v69
	v_add_f32_e32 v82, v82, v83
	v_pk_fma_f32 v[74:75], v[110:111], v[78:79], v[70:71]
	v_add_f32_dpp v68, v68, v68 quad_perm:[1,0,3,2] row_mask:0xf bank_mask:0xf bound_ctrl:1
	v_add_f32_dpp v82, v82, v82 row_ror:8 row_mask:0xf bank_mask:0xf bound_ctrl:1
	v_pk_fma_f32 v[76:77], v[112:113], v[80:81], v[72:73]
	v_add_f32_dpp v68, v68, v68 quad_perm:[2,3,0,1] row_mask:0xf bank_mask:0xf bound_ctrl:1
	ds_read_b128 v[24:27], v84 offset:5376
	v_add_f32_dpp v68, v68, v68 row_half_mirror row_mask:0xf bank_mask:0xf bound_ctrl:1
	ds_read_b128 v[28:31], v84 offset:13568
	ds_read_b128 v[32:35], v84 offset:21760
	v_add_f32_dpp v68, v68, v68 row_ror:8 row_mask:0xf bank_mask:0xf bound_ctrl:1
	ds_read_b128 v[36:39], v84 offset:29952
	ds_read_b128 v[40:43], v84 offset:38144
	ds_read_b32 v44, v85 offset:42304
	v_pk_fma_f32 v[78:79], v[114:115], v[68:69], v[74:75] op_sel_hi:[1,0,1] neg_lo:[0,1,0] neg_hi:[0,1,0]
	v_pk_fma_f32 v[80:81], v[116:117], v[68:69], v[76:77] op_sel_hi:[1,0,1] neg_lo:[0,1,0] neg_hi:[0,1,0]
	s_waitcnt lgkmcnt(6)
	v_pk_mul_f32 v[68:69], v[2:3], v[78:79]
	v_pk_mul_f32 v[88:89], v[122:123], v[78:79]
	v_pk_mul_f32 v[70:71], v[22:23], v[14:15] op_sel_hi:[0,1]
	v_pk_fma_f32 v[68:69], v[4:5], v[80:81], v[68:69]
	v_pk_fma_f32 v[88:89], v[124:125], v[80:81], v[88:89]
	v_pk_mul_f32 v[72:73], v[22:23], v[16:17] op_sel_hi:[0,1]
	v_add_f32_e32 v68, v68, v69
	v_add_f32_e32 v88, v88, v89
	v_pk_fma_f32 v[74:75], v[6:7], v[78:79], v[70:71]
	v_add_f32_dpp v68, v68, v68 quad_perm:[1,0,3,2] row_mask:0xf bank_mask:0xf bound_ctrl:1
	v_add_f32_dpp v88, v88, v88 row_ror:8 row_mask:0xf bank_mask:0xf bound_ctrl:1
	v_pk_fma_f32 v[76:77], v[8:9], v[80:81], v[72:73]
	v_add_f32_dpp v68, v68, v68 quad_perm:[2,3,0,1] row_mask:0xf bank_mask:0xf bound_ctrl:1
	ds_write2st64_b32 v86, v82, v88 offset0:36 offset1:38
	ds_read_b128 v[46:49], v84 offset:5632
	v_add_f32_dpp v68, v68, v68 row_half_mirror row_mask:0xf bank_mask:0xf bound_ctrl:1
	ds_read_b128 v[50:53], v84 offset:13824
	ds_read_b128 v[54:57], v84 offset:22016
	v_add_f32_dpp v68, v68, v68 row_ror:8 row_mask:0xf bank_mask:0xf bound_ctrl:1
	ds_read_b128 v[58:61], v84 offset:30208
	ds_read_b128 v[62:65], v84 offset:38400
	ds_read_b32 v66, v85 offset:42368
	v_pk_fma_f32 v[78:79], v[10:11], v[68:69], v[74:75] op_sel_hi:[1,0,1] neg_lo:[0,1,0] neg_hi:[0,1,0]
	v_pk_fma_f32 v[80:81], v[12:13], v[68:69], v[76:77] op_sel_hi:[1,0,1] neg_lo:[0,1,0] neg_hi:[0,1,0]
	s_waitcnt lgkmcnt(6)
	v_pk_mul_f32 v[68:69], v[24:25], v[78:79]
	v_pk_mul_f32 v[82:83], v[18:19], v[78:79]
	v_pk_mul_f32 v[70:71], v[44:45], v[36:37] op_sel_hi:[0,1]
	v_pk_fma_f32 v[68:69], v[26:27], v[80:81], v[68:69]
	v_pk_fma_f32 v[82:83], v[20:21], v[80:81], v[82:83]
	v_pk_mul_f32 v[72:73], v[44:45], v[38:39] op_sel_hi:[0,1]
	v_add_f32_e32 v68, v68, v69
	v_add_f32_e32 v82, v82, v83
	v_pk_fma_f32 v[74:75], v[28:29], v[78:79], v[70:71]
	v_add_f32_dpp v68, v68, v68 quad_perm:[1,0,3,2] row_mask:0xf bank_mask:0xf bound_ctrl:1
	v_add_f32_dpp v82, v82, v82 row_ror:8 row_mask:0xf bank_mask:0xf bound_ctrl:1
	v_pk_fma_f32 v[76:77], v[30:31], v[80:81], v[72:73]
	v_add_f32_dpp v68, v68, v68 quad_perm:[2,3,0,1] row_mask:0xf bank_mask:0xf bound_ctrl:1
	ds_read_b128 v[106:109], v84 offset:5888
	v_add_f32_dpp v68, v68, v68 row_half_mirror row_mask:0xf bank_mask:0xf bound_ctrl:1
	ds_read_b128 v[110:113], v84 offset:14080
	ds_read_b128 v[114:117], v84 offset:22272
	v_add_f32_dpp v68, v68, v68 row_ror:8 row_mask:0xf bank_mask:0xf bound_ctrl:1
	ds_read_b128 v[118:121], v84 offset:30464
	ds_read_b128 v[122:125], v84 offset:38656
	ds_read_b32 v126, v85 offset:42432
	v_pk_fma_f32 v[78:79], v[32:33], v[68:69], v[74:75] op_sel_hi:[1,0,1] neg_lo:[0,1,0] neg_hi:[0,1,0]
	v_pk_fma_f32 v[80:81], v[34:35], v[68:69], v[76:77] op_sel_hi:[1,0,1] neg_lo:[0,1,0] neg_hi:[0,1,0]
	s_waitcnt lgkmcnt(6)
	v_pk_mul_f32 v[68:69], v[46:47], v[78:79]
	v_pk_mul_f32 v[88:89], v[40:41], v[78:79]
	v_pk_mul_f32 v[70:71], v[66:67], v[58:59] op_sel_hi:[0,1]
	v_pk_fma_f32 v[68:69], v[48:49], v[80:81], v[68:69]
	v_pk_fma_f32 v[88:89], v[42:43], v[80:81], v[88:89]
	v_pk_mul_f32 v[72:73], v[66:67], v[60:61] op_sel_hi:[0,1]
	v_add_f32_e32 v68, v68, v69
	v_add_f32_e32 v88, v88, v89
	v_pk_fma_f32 v[74:75], v[50:51], v[78:79], v[70:71]
	v_add_f32_dpp v68, v68, v68 quad_perm:[1,0,3,2] row_mask:0xf bank_mask:0xf bound_ctrl:1
	v_add_f32_dpp v88, v88, v88 row_ror:8 row_mask:0xf bank_mask:0xf bound_ctrl:1
	v_pk_fma_f32 v[76:77], v[52:53], v[80:81], v[72:73]
	v_add_f32_dpp v68, v68, v68 quad_perm:[2,3,0,1] row_mask:0xf bank_mask:0xf bound_ctrl:1
	ds_write2st64_b32 v86, v82, v88 offset0:40 offset1:42
	ds_read_b128 v[2:5], v84 offset:6144
	v_add_f32_dpp v68, v68, v68 row_half_mirror row_mask:0xf bank_mask:0xf bound_ctrl:1
	ds_read_b128 v[6:9], v84 offset:14336
	ds_read_b128 v[10:13], v84 offset:22528
	v_add_f32_dpp v68, v68, v68 row_ror:8 row_mask:0xf bank_mask:0xf bound_ctrl:1
	ds_read_b128 v[14:17], v84 offset:30720
	ds_read_b128 v[18:21], v84 offset:38912
	ds_read_b32 v22, v85 offset:42496
	v_pk_fma_f32 v[78:79], v[54:55], v[68:69], v[74:75] op_sel_hi:[1,0,1] neg_lo:[0,1,0] neg_hi:[0,1,0]
	v_pk_fma_f32 v[80:81], v[56:57], v[68:69], v[76:77] op_sel_hi:[1,0,1] neg_lo:[0,1,0] neg_hi:[0,1,0]
	s_waitcnt lgkmcnt(6)
	v_pk_mul_f32 v[68:69], v[106:107], v[78:79]
	v_pk_mul_f32 v[82:83], v[62:63], v[78:79]
	v_pk_mul_f32 v[70:71], v[126:127], v[118:119] op_sel_hi:[0,1]
	v_pk_fma_f32 v[68:69], v[108:109], v[80:81], v[68:69]
	v_pk_fma_f32 v[82:83], v[64:65], v[80:81], v[82:83]
	v_pk_mul_f32 v[72:73], v[126:127], v[120:121] op_sel_hi:[0,1]
	v_add_f32_e32 v68, v68, v69
	v_add_f32_e32 v82, v82, v83
	v_pk_fma_f32 v[74:75], v[110:111], v[78:79], v[70:71]
	v_add_f32_dpp v68, v68, v68 quad_perm:[1,0,3,2] row_mask:0xf bank_mask:0xf bound_ctrl:1
	v_add_f32_dpp v82, v82, v82 row_ror:8 row_mask:0xf bank_mask:0xf bound_ctrl:1
	v_pk_fma_f32 v[76:77], v[112:113], v[80:81], v[72:73]
	v_add_f32_dpp v68, v68, v68 quad_perm:[2,3,0,1] row_mask:0xf bank_mask:0xf bound_ctrl:1
	ds_read_b128 v[24:27], v84 offset:6400
	v_add_f32_dpp v68, v68, v68 row_half_mirror row_mask:0xf bank_mask:0xf bound_ctrl:1
	ds_read_b128 v[28:31], v84 offset:14592
	ds_read_b128 v[32:35], v84 offset:22784
	v_add_f32_dpp v68, v68, v68 row_ror:8 row_mask:0xf bank_mask:0xf bound_ctrl:1
	ds_read_b128 v[36:39], v84 offset:30976
	ds_read_b128 v[40:43], v84 offset:39168
	ds_read_b32 v44, v85 offset:42560
	v_pk_fma_f32 v[78:79], v[114:115], v[68:69], v[74:75] op_sel_hi:[1,0,1] neg_lo:[0,1,0] neg_hi:[0,1,0]
	v_pk_fma_f32 v[80:81], v[116:117], v[68:69], v[76:77] op_sel_hi:[1,0,1] neg_lo:[0,1,0] neg_hi:[0,1,0]
	s_waitcnt lgkmcnt(6)
	v_pk_mul_f32 v[68:69], v[2:3], v[78:79]
	v_pk_mul_f32 v[88:89], v[122:123], v[78:79]
	v_pk_mul_f32 v[70:71], v[22:23], v[14:15] op_sel_hi:[0,1]
	v_pk_fma_f32 v[68:69], v[4:5], v[80:81], v[68:69]
	v_pk_fma_f32 v[88:89], v[124:125], v[80:81], v[88:89]
	v_pk_mul_f32 v[72:73], v[22:23], v[16:17] op_sel_hi:[0,1]
	v_add_f32_e32 v68, v68, v69
	v_add_f32_e32 v88, v88, v89
	v_pk_fma_f32 v[74:75], v[6:7], v[78:79], v[70:71]
	v_add_f32_dpp v68, v68, v68 quad_perm:[1,0,3,2] row_mask:0xf bank_mask:0xf bound_ctrl:1
	v_add_f32_dpp v88, v88, v88 row_ror:8 row_mask:0xf bank_mask:0xf bound_ctrl:1
	v_pk_fma_f32 v[76:77], v[8:9], v[80:81], v[72:73]
	v_add_f32_dpp v68, v68, v68 quad_perm:[2,3,0,1] row_mask:0xf bank_mask:0xf bound_ctrl:1
	ds_write2st64_b32 v86, v82, v88 offset0:44 offset1:46
	ds_read_b128 v[46:49], v84 offset:6656
	v_add_f32_dpp v68, v68, v68 row_half_mirror row_mask:0xf bank_mask:0xf bound_ctrl:1
	ds_read_b128 v[50:53], v84 offset:14848
	ds_read_b128 v[54:57], v84 offset:23040
	v_add_f32_dpp v68, v68, v68 row_ror:8 row_mask:0xf bank_mask:0xf bound_ctrl:1
	ds_read_b128 v[58:61], v84 offset:31232
	ds_read_b128 v[62:65], v84 offset:39424
	ds_read_b32 v66, v85 offset:42624
	v_pk_fma_f32 v[78:79], v[10:11], v[68:69], v[74:75] op_sel_hi:[1,0,1] neg_lo:[0,1,0] neg_hi:[0,1,0]
	v_pk_fma_f32 v[80:81], v[12:13], v[68:69], v[76:77] op_sel_hi:[1,0,1] neg_lo:[0,1,0] neg_hi:[0,1,0]
	s_waitcnt lgkmcnt(6)
	v_pk_mul_f32 v[68:69], v[24:25], v[78:79]
	v_pk_mul_f32 v[82:83], v[18:19], v[78:79]
	v_pk_mul_f32 v[70:71], v[44:45], v[36:37] op_sel_hi:[0,1]
	v_pk_fma_f32 v[68:69], v[26:27], v[80:81], v[68:69]
	v_pk_fma_f32 v[82:83], v[20:21], v[80:81], v[82:83]
	v_pk_mul_f32 v[72:73], v[44:45], v[38:39] op_sel_hi:[0,1]
	v_add_f32_e32 v68, v68, v69
	v_add_f32_e32 v82, v82, v83
	v_pk_fma_f32 v[74:75], v[28:29], v[78:79], v[70:71]
	v_add_f32_dpp v68, v68, v68 quad_perm:[1,0,3,2] row_mask:0xf bank_mask:0xf bound_ctrl:1
	v_add_f32_dpp v82, v82, v82 row_ror:8 row_mask:0xf bank_mask:0xf bound_ctrl:1
	v_pk_fma_f32 v[76:77], v[30:31], v[80:81], v[72:73]
	v_add_f32_dpp v68, v68, v68 quad_perm:[2,3,0,1] row_mask:0xf bank_mask:0xf bound_ctrl:1
	ds_read_b128 v[106:109], v84 offset:6912
	v_add_f32_dpp v68, v68, v68 row_half_mirror row_mask:0xf bank_mask:0xf bound_ctrl:1
	ds_read_b128 v[110:113], v84 offset:15104
	ds_read_b128 v[114:117], v84 offset:23296
	v_add_f32_dpp v68, v68, v68 row_ror:8 row_mask:0xf bank_mask:0xf bound_ctrl:1
	ds_read_b128 v[118:121], v84 offset:31488
	ds_read_b128 v[122:125], v84 offset:39680
	ds_read_b32 v126, v85 offset:42688
	v_pk_fma_f32 v[78:79], v[32:33], v[68:69], v[74:75] op_sel_hi:[1,0,1] neg_lo:[0,1,0] neg_hi:[0,1,0]
	v_pk_fma_f32 v[80:81], v[34:35], v[68:69], v[76:77] op_sel_hi:[1,0,1] neg_lo:[0,1,0] neg_hi:[0,1,0]
	s_waitcnt lgkmcnt(6)
	v_pk_mul_f32 v[68:69], v[46:47], v[78:79]
	v_pk_mul_f32 v[88:89], v[40:41], v[78:79]
	v_pk_mul_f32 v[70:71], v[66:67], v[58:59] op_sel_hi:[0,1]
	v_pk_fma_f32 v[68:69], v[48:49], v[80:81], v[68:69]
	v_pk_fma_f32 v[88:89], v[42:43], v[80:81], v[88:89]
	v_pk_mul_f32 v[72:73], v[66:67], v[60:61] op_sel_hi:[0,1]
	v_add_f32_e32 v68, v68, v69
	v_add_f32_e32 v88, v88, v89
	v_pk_fma_f32 v[74:75], v[50:51], v[78:79], v[70:71]
	v_add_f32_dpp v68, v68, v68 quad_perm:[1,0,3,2] row_mask:0xf bank_mask:0xf bound_ctrl:1
	v_add_f32_dpp v88, v88, v88 row_ror:8 row_mask:0xf bank_mask:0xf bound_ctrl:1
	v_pk_fma_f32 v[76:77], v[52:53], v[80:81], v[72:73]
	v_add_f32_dpp v68, v68, v68 quad_perm:[2,3,0,1] row_mask:0xf bank_mask:0xf bound_ctrl:1
	ds_write2st64_b32 v86, v82, v88 offset0:48 offset1:50
	ds_read_b128 v[2:5], v84 offset:7168
	v_add_f32_dpp v68, v68, v68 row_half_mirror row_mask:0xf bank_mask:0xf bound_ctrl:1
	ds_read_b128 v[6:9], v84 offset:15360
	ds_read_b128 v[10:13], v84 offset:23552
	v_add_f32_dpp v68, v68, v68 row_ror:8 row_mask:0xf bank_mask:0xf bound_ctrl:1
	ds_read_b128 v[14:17], v84 offset:31744
	ds_read_b128 v[18:21], v84 offset:39936
	ds_read_b32 v22, v85 offset:42752
	v_pk_fma_f32 v[78:79], v[54:55], v[68:69], v[74:75] op_sel_hi:[1,0,1] neg_lo:[0,1,0] neg_hi:[0,1,0]
	v_pk_fma_f32 v[80:81], v[56:57], v[68:69], v[76:77] op_sel_hi:[1,0,1] neg_lo:[0,1,0] neg_hi:[0,1,0]
	s_waitcnt lgkmcnt(6)
	v_pk_mul_f32 v[68:69], v[106:107], v[78:79]
	v_pk_mul_f32 v[82:83], v[62:63], v[78:79]
	v_pk_mul_f32 v[70:71], v[126:127], v[118:119] op_sel_hi:[0,1]
	v_pk_fma_f32 v[68:69], v[108:109], v[80:81], v[68:69]
	v_pk_fma_f32 v[82:83], v[64:65], v[80:81], v[82:83]
	v_pk_mul_f32 v[72:73], v[126:127], v[120:121] op_sel_hi:[0,1]
	v_add_f32_e32 v68, v68, v69
	v_add_f32_e32 v82, v82, v83
	v_pk_fma_f32 v[74:75], v[110:111], v[78:79], v[70:71]
	v_add_f32_dpp v68, v68, v68 quad_perm:[1,0,3,2] row_mask:0xf bank_mask:0xf bound_ctrl:1
	v_add_f32_dpp v82, v82, v82 row_ror:8 row_mask:0xf bank_mask:0xf bound_ctrl:1
	v_pk_fma_f32 v[76:77], v[112:113], v[80:81], v[72:73]
	v_add_f32_dpp v68, v68, v68 quad_perm:[2,3,0,1] row_mask:0xf bank_mask:0xf bound_ctrl:1
	ds_read_b128 v[24:27], v84 offset:7424
	v_add_f32_dpp v68, v68, v68 row_half_mirror row_mask:0xf bank_mask:0xf bound_ctrl:1
	ds_read_b128 v[28:31], v84 offset:15616
	ds_read_b128 v[32:35], v84 offset:23808
	v_add_f32_dpp v68, v68, v68 row_ror:8 row_mask:0xf bank_mask:0xf bound_ctrl:1
	ds_read_b128 v[36:39], v84 offset:32000
	ds_read_b128 v[40:43], v84 offset:40192
	ds_read_b32 v44, v85 offset:42816
	v_pk_fma_f32 v[78:79], v[114:115], v[68:69], v[74:75] op_sel_hi:[1,0,1] neg_lo:[0,1,0] neg_hi:[0,1,0]
	v_pk_fma_f32 v[80:81], v[116:117], v[68:69], v[76:77] op_sel_hi:[1,0,1] neg_lo:[0,1,0] neg_hi:[0,1,0]
	s_waitcnt lgkmcnt(6)
	v_pk_mul_f32 v[68:69], v[2:3], v[78:79]
	v_pk_mul_f32 v[88:89], v[122:123], v[78:79]
	v_pk_mul_f32 v[70:71], v[22:23], v[14:15] op_sel_hi:[0,1]
	v_pk_fma_f32 v[68:69], v[4:5], v[80:81], v[68:69]
	v_pk_fma_f32 v[88:89], v[124:125], v[80:81], v[88:89]
	v_pk_mul_f32 v[72:73], v[22:23], v[16:17] op_sel_hi:[0,1]
	v_add_f32_e32 v68, v68, v69
	v_add_f32_e32 v88, v88, v89
	v_pk_fma_f32 v[74:75], v[6:7], v[78:79], v[70:71]
	v_add_f32_dpp v68, v68, v68 quad_perm:[1,0,3,2] row_mask:0xf bank_mask:0xf bound_ctrl:1
	v_add_f32_dpp v88, v88, v88 row_ror:8 row_mask:0xf bank_mask:0xf bound_ctrl:1
	v_pk_fma_f32 v[76:77], v[8:9], v[80:81], v[72:73]
	v_add_f32_dpp v68, v68, v68 quad_perm:[2,3,0,1] row_mask:0xf bank_mask:0xf bound_ctrl:1
	ds_write2st64_b32 v86, v82, v88 offset0:52 offset1:54
	ds_read_b128 v[46:49], v84 offset:7680
	v_add_f32_dpp v68, v68, v68 row_half_mirror row_mask:0xf bank_mask:0xf bound_ctrl:1
	ds_read_b128 v[50:53], v84 offset:15872
	ds_read_b128 v[54:57], v84 offset:24064
	v_add_f32_dpp v68, v68, v68 row_ror:8 row_mask:0xf bank_mask:0xf bound_ctrl:1
	ds_read_b128 v[58:61], v84 offset:32256
	ds_read_b128 v[62:65], v84 offset:40448
	ds_read_b32 v66, v85 offset:42880
	v_pk_fma_f32 v[78:79], v[10:11], v[68:69], v[74:75] op_sel_hi:[1,0,1] neg_lo:[0,1,0] neg_hi:[0,1,0]
	v_pk_fma_f32 v[80:81], v[12:13], v[68:69], v[76:77] op_sel_hi:[1,0,1] neg_lo:[0,1,0] neg_hi:[0,1,0]
	s_waitcnt lgkmcnt(6)
	v_pk_mul_f32 v[68:69], v[24:25], v[78:79]
	v_pk_mul_f32 v[82:83], v[18:19], v[78:79]
	v_pk_mul_f32 v[70:71], v[44:45], v[36:37] op_sel_hi:[0,1]
	v_pk_fma_f32 v[68:69], v[26:27], v[80:81], v[68:69]
	v_pk_fma_f32 v[82:83], v[20:21], v[80:81], v[82:83]
	v_pk_mul_f32 v[72:73], v[44:45], v[38:39] op_sel_hi:[0,1]
	v_add_f32_e32 v68, v68, v69
	v_add_f32_e32 v82, v82, v83
	v_pk_fma_f32 v[74:75], v[28:29], v[78:79], v[70:71]
	v_add_f32_dpp v68, v68, v68 quad_perm:[1,0,3,2] row_mask:0xf bank_mask:0xf bound_ctrl:1
	v_add_f32_dpp v82, v82, v82 row_ror:8 row_mask:0xf bank_mask:0xf bound_ctrl:1
	v_pk_fma_f32 v[76:77], v[30:31], v[80:81], v[72:73]
	v_add_f32_dpp v68, v68, v68 quad_perm:[2,3,0,1] row_mask:0xf bank_mask:0xf bound_ctrl:1
	ds_read_b128 v[106:109], v84 offset:7936
	v_add_f32_dpp v68, v68, v68 row_half_mirror row_mask:0xf bank_mask:0xf bound_ctrl:1
	ds_read_b128 v[110:113], v84 offset:16128
	ds_read_b128 v[114:117], v84 offset:24320
	v_add_f32_dpp v68, v68, v68 row_ror:8 row_mask:0xf bank_mask:0xf bound_ctrl:1
	ds_read_b128 v[118:121], v84 offset:32512
	ds_read_b128 v[122:125], v84 offset:40704
	ds_read_b32 v126, v85 offset:42944
	v_pk_fma_f32 v[78:79], v[32:33], v[68:69], v[74:75] op_sel_hi:[1,0,1] neg_lo:[0,1,0] neg_hi:[0,1,0]
	v_pk_fma_f32 v[80:81], v[34:35], v[68:69], v[76:77] op_sel_hi:[1,0,1] neg_lo:[0,1,0] neg_hi:[0,1,0]
	s_waitcnt lgkmcnt(6)
	v_pk_mul_f32 v[68:69], v[46:47], v[78:79]
	v_pk_mul_f32 v[88:89], v[40:41], v[78:79]
	v_pk_mul_f32 v[70:71], v[66:67], v[58:59] op_sel_hi:[0,1]
	v_pk_fma_f32 v[68:69], v[48:49], v[80:81], v[68:69]
	v_pk_fma_f32 v[88:89], v[42:43], v[80:81], v[88:89]
	v_pk_mul_f32 v[72:73], v[66:67], v[60:61] op_sel_hi:[0,1]
	v_add_f32_e32 v68, v68, v69
	v_add_f32_e32 v88, v88, v89
	v_pk_fma_f32 v[74:75], v[50:51], v[78:79], v[70:71]
	v_add_f32_dpp v68, v68, v68 quad_perm:[1,0,3,2] row_mask:0xf bank_mask:0xf bound_ctrl:1
	v_add_f32_dpp v88, v88, v88 row_ror:8 row_mask:0xf bank_mask:0xf bound_ctrl:1
	v_pk_fma_f32 v[76:77], v[52:53], v[80:81], v[72:73]
	v_add_f32_dpp v68, v68, v68 quad_perm:[2,3,0,1] row_mask:0xf bank_mask:0xf bound_ctrl:1
	ds_write2st64_b32 v86, v82, v88 offset0:56 offset1:58
	s_nop 1
	v_add_f32_dpp v68, v68, v68 row_half_mirror row_mask:0xf bank_mask:0xf bound_ctrl:1
	s_nop 1
	v_add_f32_dpp v68, v68, v68 row_ror:8 row_mask:0xf bank_mask:0xf bound_ctrl:1
	v_pk_fma_f32 v[78:79], v[54:55], v[68:69], v[74:75] op_sel_hi:[1,0,1] neg_lo:[0,1,0] neg_hi:[0,1,0]
	v_pk_fma_f32 v[80:81], v[56:57], v[68:69], v[76:77] op_sel_hi:[1,0,1] neg_lo:[0,1,0] neg_hi:[0,1,0]
	s_waitcnt lgkmcnt(1)
	v_pk_mul_f32 v[68:69], v[106:107], v[78:79]
	v_pk_mul_f32 v[82:83], v[62:63], v[78:79]
	v_pk_mul_f32 v[70:71], v[126:127], v[118:119] op_sel_hi:[0,1]
	v_pk_fma_f32 v[68:69], v[108:109], v[80:81], v[68:69]
	v_pk_fma_f32 v[82:83], v[64:65], v[80:81], v[82:83]
	v_pk_mul_f32 v[72:73], v[126:127], v[120:121] op_sel_hi:[0,1]
	v_add_f32_e32 v68, v68, v69
	v_add_f32_e32 v82, v82, v83
	v_pk_fma_f32 v[74:75], v[110:111], v[78:79], v[70:71]
	v_add_f32_dpp v68, v68, v68 quad_perm:[1,0,3,2] row_mask:0xf bank_mask:0xf bound_ctrl:1
	v_add_f32_dpp v82, v82, v82 row_ror:8 row_mask:0xf bank_mask:0xf bound_ctrl:1
	v_pk_fma_f32 v[76:77], v[112:113], v[80:81], v[72:73]
	v_add_f32_dpp v68, v68, v68 quad_perm:[2,3,0,1] row_mask:0xf bank_mask:0xf bound_ctrl:1
	s_nop 1
	v_add_f32_dpp v68, v68, v68 row_half_mirror row_mask:0xf bank_mask:0xf bound_ctrl:1
	s_nop 1
	v_add_f32_dpp v68, v68, v68 row_ror:8 row_mask:0xf bank_mask:0xf bound_ctrl:1
	v_pk_fma_f32 v[78:79], v[114:115], v[68:69], v[74:75] op_sel_hi:[1,0,1] neg_lo:[0,1,0] neg_hi:[0,1,0]
	v_pk_fma_f32 v[80:81], v[116:117], v[68:69], v[76:77] op_sel_hi:[1,0,1] neg_lo:[0,1,0] neg_hi:[0,1,0]
	v_pk_mul_f32 v[88:89], v[122:123], v[78:79]
	v_pk_fma_f32 v[88:89], v[124:125], v[80:81], v[88:89]
	v_add_f32_e32 v88, v88, v89
	s_nop 1
	v_add_f32_dpp v88, v88, v88 row_ror:8 row_mask:0xf bank_mask:0xf bound_ctrl:1
	ds_write2st64_b32 v86, v82, v88 offset0:60 offset1:62
	v_add_u32_e32 v101, 1, v101
